# up-GEMM epilogue fast path also drops the 32 vcc-masked boundary selects (202 selects removed in total) + bias fold + bound_ctrl
# baseline (speedup 1.0000x reference)
;     __device__ __forceinline__ void operator()(const f32x4 (&acc)[2][2][4][2], const Unit& u, int wr, int wc, int fr, int fq) const {
;     ...
;                 for (int i = 0; i < 8; ++i) { xg[i] = acc[i >> 2][0][i & 3][n][j] * rs[i]; xv[i] = acc[i >> 2][1][i & 3][n][j] * rs[i]; }
;                 const float gp = __builtin_bit_cast(float, __builtin_amdgcn_update_dpp(0, __builtin_bit_cast(int, xg[7]), 0x111, 0xf, 0xf, false));
;                 const float gn = __builtin_bit_cast(float, __builtin_amdgcn_update_dpp(0, __builtin_bit_cast(int, xg[0]), 0x101, 0xf, 0xf, false));
;                 const float vp = __builtin_bit_cast(float, __builtin_amdgcn_update_dpp(0, __builtin_bit_cast(int, xv[7]), 0x111, 0xf, 0xf, false));
;                 const float vn = __builtin_bit_cast(float, __builtin_amdgcn_update_dpp(0, __builtin_bit_cast(int, xv[0]), 0x101, 0xf, 0xf, false));
; #pragma unroll
;                 for (int i = 0; i < 8; ++i) {
;                     float pg = i > 0 ? xg[i - 1] : gp, ng = i < 7 ? xg[i + 1] : gn, pv = i > 0 ? xv[i - 1] : vp, nv = i < 7 ? xv[i + 1] : vn;
;                     if (pz[i]) { pg = 0.f; pv = 0.f; } if (nz[i]) { ng = 0.f; nv = 0.f; }
;                     const float cgv = gw0 * pg + gw1 * xg[i] + gw2 * ng + gb;
;                     const float cvv = vw0 * pv + vw1 * xv[i] + vw2 * nv + vb;
;                     res[i][j] = gelu_tanh(cgv) * cvv;
;                 }
;             }
; #pragma unroll
;             for (int i = 0; i < 8; ++i) { const int s = 8 * fr + i, grow = grow0 + i;
;                 if (s >= 1 && s <= 126 && grow < HALF_TOK) { u32x2 w; w.x = pk2(res[i][0], res[i][1]); w.y = pk2(res[i][2], res[i][3]); *(u32x2*)(G + (size_t)grow * DFF + cg0 + 4 * n) = w; } }
.Lupf_600:
	s_or_b64 exec, exec, s[10:11]
	v_and_b32_e32 v152, 0x1fff, v191
	s_movk_i32 s10, 0x3fff
	v_cmp_eq_u32_e32 vcc, 0, v152
	v_pk_mul_f32 v[160:161], v[102:103], v[196:197] op_sel_hi:[1, 0]
	v_pk_mul_f32 v[152:153], v[98:99], v[196:197] op_sel_hi:[1, 0]
	v_pk_mul_f32 v[102:103], v[104:105], v[196:197] op_sel_hi:[1, 0]
	v_pk_mul_f32 v[98:99], v[100:101], v[196:197] op_sel_hi:[1, 0]
	v_add_u32_e32 v191, 1, v189
	v_cmp_gt_i32_e64 s[14:15], s10, v189
	s_and_saveexec_b64 s[10:11], s[14:15]
	s_cbranch_execz .Lupf_602
	v_pk_fma_f32 v[232:233], v[222:223], v[122:123], v[118:119]
	v_pk_fma_f32 v[100:101], v[228:229], v[106:107], v[232:233]
	v_pk_fma_f32 v[100:101], v[160:161], v[110:111], v[100:101]
	v_pk_mul_f32 v[228:229], v[100:101], v[100:101]
	v_fmamk_f32 v203, v228, 0xbdd2d3e8, v245
	v_mul_f32_e32 v203, v100, v203
	v_fmamk_f32 v228, v229, 0xbdd2d3e8, v245
	v_exp_f32_e32 v203, v203
	v_mul_f32_e32 v228, v101, v228
	v_exp_f32_e32 v233, v228
	v_pk_fma_f32 v[228:229], v[220:221], v[126:127], v[138:139]
	v_add_f32_e32 v203, 1.0, v203
	v_rcp_f32_e32 v232, v203
	v_add_f32_e32 v203, 1.0, v233
	v_rcp_f32_e32 v233, v203
	v_pk_fma_f32 v[104:105], v[230:231], v[114:115], v[228:229]
	v_pk_fma_f32 v[104:105], v[152:153], v[130:131], v[104:105]
	v_pk_mul_f32 v[100:101], v[100:101], v[232:233]
	v_pk_fma_f32 v[230:231], v[156:157], v[124:125], v[120:121]
	v_pk_mul_f32 v[100:101], v[104:105], v[100:101]
	v_mov_b32_e32 v105, v225
	v_mov_b32_e32 v104, v224
	v_mov_b32_e32 v225, v227
	v_mov_b32_e32 v224, v226
	v_pk_fma_f32 v[104:105], v[104:105], v[108:109], v[230:231]
	v_pk_fma_f32 v[104:105], v[102:103], v[112:113], v[104:105]
	v_cvt_pk_bf16_f32 v100, v100, v101
	s_nop 0
	v_pk_mul_f32 v[226:227], v[104:105], v[104:105]
	s_nop 0
	v_fmamk_f32 v203, v226, 0xbdd2d3e8, v245
	v_mul_f32_e32 v203, v104, v203
	v_fmamk_f32 v226, v227, 0xbdd2d3e8, v245
	v_exp_f32_e32 v203, v203
	v_mul_f32_e32 v226, v105, v226
	v_exp_f32_e32 v231, v226
	v_pk_fma_f32 v[226:227], v[150:151], v[128:129], v[140:141]
	v_add_f32_e32 v203, 1.0, v203
	v_rcp_f32_e32 v230, v203
	v_add_f32_e32 v203, 1.0, v231
	v_rcp_f32_e32 v231, v203
	v_pk_fma_f32 v[224:225], v[224:225], v[116:117], v[226:227]
	v_pk_mul_f32 v[104:105], v[104:105], v[230:231]
	v_pk_fma_f32 v[224:225], v[98:99], v[132:133], v[224:225]
	s_nop 0
	s_nop 0
	v_pk_mul_f32 v[104:105], v[224:225], v[104:105]
	s_nop 0
	v_cvt_pk_bf16_f32 v101, v104, v105
	v_mov_b64_e32 v[104:105], s[34:35]
	v_mad_i64_i32 v[104:105], s[12:13], v191, s85, v[104:105]
	v_lshl_add_u64 v[104:105], v[186:187], 1, v[104:105]
	global_store_dwordx2 v[104:105], v[100:101], off
.Lupf_602:
	s_or_b64 exec, exec, s[10:11]
	v_and_b32_e32 v100, 0x1fff, v193
	v_cmp_eq_u32_e64 s[10:11], 0, v100
	v_cmp_ne_u32_e64 s[12:13], s67, v193
	s_and_b64 s[96:97], s[12:13], s[10:11]
	s_movk_i32 s10, 0x3ffe
	v_pk_mul_f32 v[104:105], v[94:95], v[194:195] op_sel_hi:[1, 0]
	v_pk_mul_f32 v[100:101], v[90:91], v[194:195] op_sel_hi:[1, 0]
	v_pk_mul_f32 v[94:95], v[96:97], v[194:195] op_sel_hi:[1, 0]
	v_pk_mul_f32 v[90:91], v[92:93], v[194:195] op_sel_hi:[1, 0]
	v_add_u32_e32 v193, 2, v189
	v_cmp_gt_i32_e64 s[16:17], s10, v189
	s_and_saveexec_b64 s[10:11], s[16:17]
	s_cbranch_execz .Lupf_604
	v_pk_fma_f32 v[224:225], v[160:161], v[122:123], v[118:119]
	v_mov_b32_e32 v97, v221
	v_mov_b32_e32 v96, v220
	v_pk_fma_f32 v[92:93], v[222:223], v[106:107], v[224:225]
	v_pk_fma_f32 v[92:93], v[104:105], v[110:111], v[92:93]
	v_pk_mul_f32 v[220:221], v[92:93], v[92:93]
	v_fmamk_f32 v203, v220, 0xbdd2d3e8, v245
	v_mul_f32_e32 v203, v92, v203
	v_fmamk_f32 v220, v221, 0xbdd2d3e8, v245
	v_exp_f32_e32 v203, v203
	v_mul_f32_e32 v220, v93, v220
	v_exp_f32_e32 v225, v220
	v_pk_fma_f32 v[220:221], v[152:153], v[126:127], v[138:139]
	v_add_f32_e32 v203, 1.0, v203
	v_rcp_f32_e32 v224, v203
	v_add_f32_e32 v203, 1.0, v225
	v_rcp_f32_e32 v225, v203
	v_pk_fma_f32 v[96:97], v[96:97], v[114:115], v[220:221]
	v_pk_fma_f32 v[96:97], v[100:101], v[130:131], v[96:97]
	v_pk_mul_f32 v[92:93], v[92:93], v[224:225]
	v_pk_fma_f32 v[222:223], v[102:103], v[124:125], v[120:121]
	v_pk_mul_f32 v[92:93], v[96:97], v[92:93]
	v_pk_fma_f32 v[96:97], v[156:157], v[108:109], v[222:223]
	v_pk_fma_f32 v[96:97], v[94:95], v[112:113], v[96:97]
	v_cvt_pk_bf16_f32 v92, v92, v93
	s_nop 0
	v_pk_mul_f32 v[156:157], v[96:97], v[96:97]
	s_nop 0
	v_fmamk_f32 v156, v156, 0xbdd2d3e8, v245
	v_mul_f32_e32 v156, v96, v156
	v_exp_f32_e32 v203, v156
	v_fmamk_f32 v156, v157, 0xbdd2d3e8, v245
	v_mul_f32_e32 v156, v97, v156
	v_exp_f32_e32 v223, v156
	v_add_f32_e32 v203, 1.0, v203
	v_rcp_f32_e32 v222, v203
	v_pk_fma_f32 v[156:157], v[98:99], v[128:129], v[140:141]
	v_add_f32_e32 v203, 1.0, v223
	v_rcp_f32_e32 v223, v203
	v_pk_fma_f32 v[150:151], v[150:151], v[116:117], v[156:157]
	v_pk_mul_f32 v[96:97], v[96:97], v[222:223]
	v_pk_fma_f32 v[150:151], v[90:91], v[132:133], v[150:151]
	s_nop 0
	s_nop 0
	v_pk_mul_f32 v[96:97], v[150:151], v[96:97]
	s_nop 0
	v_cvt_pk_bf16_f32 v93, v96, v97
	v_mov_b64_e32 v[96:97], s[34:35]
	v_mad_i64_i32 v[96:97], s[12:13], v193, s85, v[96:97]
	v_lshl_add_u64 v[96:97], v[186:187], 1, v[96:97]
	global_store_dwordx2 v[96:97], v[92:93], off

;     __device__ __forceinline__ void operator()(const f32x4 (&acc)[2][2][4][2], const Unit& u, int wr, int wc, int fr, int fq) const {
;     ...
;                 for (int i = 0; i < 8; ++i) { xg[i] = acc[i >> 2][0][i & 3][n][j] * rs[i]; xv[i] = acc[i >> 2][1][i & 3][n][j] * rs[i]; }
;                 const float gp = __builtin_bit_cast(float, __builtin_amdgcn_update_dpp(0, __builtin_bit_cast(int, xg[7]), 0x111, 0xf, 0xf, false));
;                 const float gn = __builtin_bit_cast(float, __builtin_amdgcn_update_dpp(0, __builtin_bit_cast(int, xg[0]), 0x101, 0xf, 0xf, false));
;                 const float vp = __builtin_bit_cast(float, __builtin_amdgcn_update_dpp(0, __builtin_bit_cast(int, xv[7]), 0x111, 0xf, 0xf, false));
;                 const float vn = __builtin_bit_cast(float, __builtin_amdgcn_update_dpp(0, __builtin_bit_cast(int, xv[0]), 0x101, 0xf, 0xf, false));
; #pragma unroll
;                 for (int i = 0; i < 8; ++i) {
;                     float pg = i > 0 ? xg[i - 1] : gp, ng = i < 7 ? xg[i + 1] : gn, pv = i > 0 ? xv[i - 1] : vp, nv = i < 7 ? xv[i + 1] : vn;
;                     if (pz[i]) { pg = 0.f; pv = 0.f; } if (nz[i]) { ng = 0.f; nv = 0.f; }
;                     const float cgv = gw0 * pg + gw1 * xg[i] + gw2 * ng + gb;
;                     const float cvv = vw0 * pv + vw1 * xv[i] + vw2 * nv + vb;
;                     res[i][j] = gelu_tanh(cgv) * cvv;
;                 }
;             }
; #pragma unroll
;             for (int i = 0; i < 8; ++i) { const int s = 8 * fr + i, grow = grow0 + i;
;                 if (s >= 1 && s <= 126 && grow < HALF_TOK) { u32x2 w; w.x = pk2(res[i][0], res[i][1]); w.y = pk2(res[i][2], res[i][3]); *(u32x2*)(G + (size_t)grow * DFF + cg0 + 4 * n) = w; } }
.Lupf_616:
	s_or_b64 exec, exec, s[68:69]
	v_mov_b32_e32 v197, v196
	v_pk_mul_f32 v[62:63], v[38:39], v[196:197]
	v_pk_mul_f32 v[56:57], v[34:35], v[196:197]
	v_pk_mul_f32 v[38:39], v[40:41], v[196:197]
	v_pk_mul_f32 v[34:35], v[36:37], v[196:197]
	s_and_saveexec_b64 s[88:89], s[14:15]
	s_cbranch_execz .Lupf_618
	s_waitcnt vmcnt(6)
	v_pk_mul_f32 v[110:111], v[102:103], v[78:79]
	v_mov_b32_e32 v41, v107
	v_mov_b32_e32 v40, v106
	v_pk_fma_f32 v[36:37], v[108:109], v[70:71], v[110:111]
	s_waitcnt vmcnt(5)
	v_pk_fma_f32 v[36:37], v[62:63], v[74:75], v[36:37]
	s_waitcnt vmcnt(4)
	v_pk_add_f32 v[36:37], v[82:83], v[36:37]
	s_nop 0
	v_pk_mul_f32 v[106:107], v[36:37], v[36:37]
	s_nop 0
	v_fmamk_f32 v106, v106, 0xbdd2d3e8, v245
	v_mul_f32_e32 v106, v36, v106
	v_exp_f32_e32 v110, v106
	v_fmamk_f32 v106, v107, 0xbdd2d3e8, v245
	v_mul_f32_e32 v106, v37, v106
	v_exp_f32_e32 v111, v106
	v_add_f32_e32 v110, 1.0, v110
	v_rcp_f32_e32 v110, v110
	s_waitcnt vmcnt(2)
	v_pk_mul_f32 v[106:107], v[100:101], v[86:87]
	v_add_f32_e32 v111, 1.0, v111
	v_rcp_f32_e32 v111, v111
	v_pk_fma_f32 v[40:41], v[40:41], v[66:67], v[106:107]
	s_waitcnt vmcnt(1)
	v_pk_fma_f32 v[40:41], v[56:57], v[90:91], v[40:41]
	v_pk_mul_f32 v[36:37], v[36:37], v[110:111]
	s_waitcnt vmcnt(0)
	v_pk_add_f32 v[40:41], v[94:95], v[40:41]
	v_pk_fma_f32 v[108:109], v[60:61], v[80:81], v[84:85]
	v_pk_mul_f32 v[36:37], v[40:41], v[36:37]
	v_mov_b32_e32 v41, v65
	v_mov_b32_e32 v40, v64
	v_mov_b32_e32 v65, v105
	v_mov_b32_e32 v64, v104
	v_pk_fma_f32 v[40:41], v[40:41], v[72:73], v[108:109]
	v_pk_fma_f32 v[40:41], v[38:39], v[76:77], v[40:41]
	v_cvt_pk_bf16_f32 v36, v36, v37
	s_nop 0
	v_pk_mul_f32 v[104:105], v[40:41], v[40:41]
	s_nop 0
	v_fmamk_f32 v104, v104, 0xbdd2d3e8, v245
	v_mul_f32_e32 v104, v40, v104
	v_exp_f32_e32 v108, v104
	v_fmamk_f32 v104, v105, 0xbdd2d3e8, v245
	v_mul_f32_e32 v104, v41, v104
	v_exp_f32_e32 v109, v104
	v_add_f32_e32 v108, 1.0, v108
	v_rcp_f32_e32 v108, v108
	v_pk_fma_f32 v[104:105], v[54:55], v[88:89], v[96:97]
	v_add_f32_e32 v109, 1.0, v109
	v_rcp_f32_e32 v109, v109
	v_pk_fma_f32 v[64:65], v[64:65], v[68:69], v[104:105]
	v_pk_mul_f32 v[40:41], v[40:41], v[108:109]
	v_pk_fma_f32 v[64:65], v[34:35], v[92:93], v[64:65]
	s_nop 0
	s_nop 0
	v_pk_mul_f32 v[40:41], v[64:65], v[40:41]
	s_nop 0
	v_cvt_pk_bf16_f32 v37, v40, v41
	v_mov_b64_e32 v[40:41], s[34:35]
	v_mad_i64_i32 v[40:41], s[14:15], v191, s85, v[40:41]
	v_lshl_add_u64 v[40:41], v[186:187], 1, v[40:41]
	global_store_dwordx2 v[40:41], v[36:37], off offset:8
.Lupf_618:
	s_or_b64 exec, exec, s[88:89]
	v_mov_b32_e32 v195, v194
	v_pk_mul_f32 v[40:41], v[30:31], v[194:195]
	v_pk_mul_f32 v[36:37], v[26:27], v[194:195]
	v_pk_mul_f32 v[30:31], v[32:33], v[194:195]
	v_pk_mul_f32 v[26:27], v[28:29], v[194:195]
	s_and_saveexec_b64 s[14:15], s[16:17]
	s_cbranch_execz .Lupf_620
	v_mov_b32_e32 v29, v103
	v_mov_b32_e32 v28, v102
	s_waitcnt vmcnt(6)
	v_pk_mul_f32 v[102:103], v[62:63], v[78:79]
	v_pk_fma_f32 v[28:29], v[28:29], v[70:71], v[102:103]
	s_waitcnt vmcnt(5)
	v_pk_fma_f32 v[28:29], v[40:41], v[74:75], v[28:29]
	s_waitcnt vmcnt(4)
	v_pk_add_f32 v[28:29], v[82:83], v[28:29]
	v_pk_mul_f32 v[64:65], v[28:29], v[28:29]
	v_fmamk_f32 v64, v64, 0xbdd2d3e8, v245
	v_mul_f32_e32 v64, v28, v64
	v_exp_f32_e32 v102, v64
	v_fmamk_f32 v64, v65, 0xbdd2d3e8, v245
	v_mul_f32_e32 v64, v29, v64
	v_exp_f32_e32 v103, v64
	v_add_f32_e32 v102, 1.0, v102
	v_rcp_f32_e32 v102, v102
	s_waitcnt vmcnt(2)
	v_pk_mul_f32 v[64:65], v[56:57], v[86:87]
	v_add_f32_e32 v103, 1.0, v103
	v_rcp_f32_e32 v103, v103
	v_pk_fma_f32 v[32:33], v[100:101], v[66:67], v[64:65]
	s_waitcnt vmcnt(1)
	v_pk_fma_f32 v[32:33], v[36:37], v[90:91], v[32:33]
	v_pk_mul_f32 v[28:29], v[28:29], v[102:103]
	s_waitcnt vmcnt(0)
	v_pk_add_f32 v[32:33], v[94:95], v[32:33]
	v_pk_fma_f32 v[100:101], v[38:39], v[80:81], v[84:85]
	v_pk_mul_f32 v[28:29], v[32:33], v[28:29]
	v_pk_fma_f32 v[32:33], v[60:61], v[72:73], v[100:101]
	v_pk_fma_f32 v[32:33], v[30:31], v[76:77], v[32:33]
	v_pk_mul_f32 v[60:61], v[32:33], v[32:33]
	v_cvt_pk_bf16_f32 v28, v28, v29
	v_fmamk_f32 v60, v60, 0xbdd2d3e8, v245
	v_mul_f32_e32 v60, v32, v60
	v_exp_f32_e32 v100, v60
	v_fmamk_f32 v60, v61, 0xbdd2d3e8, v245
	v_mul_f32_e32 v60, v33, v60
	v_exp_f32_e32 v101, v60
	v_add_f32_e32 v100, 1.0, v100
	v_rcp_f32_e32 v100, v100
	v_pk_fma_f32 v[60:61], v[34:35], v[88:89], v[96:97]
	v_add_f32_e32 v101, 1.0, v101
	v_rcp_f32_e32 v101, v101
	v_pk_fma_f32 v[54:55], v[54:55], v[68:69], v[60:61]
	v_pk_mul_f32 v[32:33], v[32:33], v[100:101]
	v_pk_fma_f32 v[54:55], v[26:27], v[92:93], v[54:55]
	s_nop 0
	s_nop 0
	v_pk_mul_f32 v[32:33], v[54:55], v[32:33]
	s_nop 0
	v_cvt_pk_bf16_f32 v29, v32, v33
	v_mov_b64_e32 v[32:33], s[34:35]
	v_mad_i64_i32 v[32:33], s[16:17], v193, s85, v[32:33]
	v_lshl_add_u64 v[32:33], v[186:187], 1, v[32:33]
	global_store_dwordx2 v[32:33], v[28:29], off offset:8
